# f21 + the 128 fp8 MFMAs issued in the plain 16x16x128 f8f6f4 form instead of the MX-scaled form with unit (0x7f) scales: identical products, one issue op less per MFMA
# speedup vs baseline: 1.0071x; 1.0071x over previous
; #define PG8_STAGE(bufoff, gbase, voff) do { _Pragma("unroll") for (int _i = 0; _i < 2; ++_i) \
;         __builtin_amdgcn_global_load_lds((const unsigned*)((const char*)(gbase) + (voff)[_i]), (LAS unsigned*)(lds + (bufoff) + ldsw + _i * 8192), 16, 0, 0); } while (0)
; #define PG8_LDA(dst, b, h) do { _Pragma("unroll") for (int m = 0; m < 4; ++m) _Pragma("unroll") for (int k = 0; k < 2; ++k) dst[m][k] = *(const LAS bf16x8*)(lds + PG8_SA(b, h) + aoff + m * 2048 + k * 1024); } while (0)
; #define PG8_LDB(dst, b, h) do { _Pragma("unroll") for (int n = 0; n < 2; ++n) _Pragma("unroll") for (int k = 0; k < 2; ++k) dst[n][k] = *(const LAS bf16x8*)(lds + PG8_SB(b, h) + boff + n * 2048 + k * 1024); } while (0)
; #define PG8_WAIT_V(n) asm volatile("s_waitcnt vmcnt(" #n ")" ::: "memory")
; template <class Epi, class Sched, bool ALIGN_EPI, bool SP2>
; __device__ __forceinline__ void gemm_phase8(LAS unsigned char* lds, const int K, const Sched& S, const Epi& E) {
;     ...
;         for (int t = 0; t < nt; t += 2) {
;             const bool last = (t == nt - 2);
;             const char* a1 = cA + (size_t)(t + 1) * kstep;
;             const char* a2 = last ? nA : cA + (size_t)(t + 2) * kstep; const char* b2 = last ? nB : cB + (size_t)(t + 2) * kstep;
;             const char* a3 = a2 + kstep; const char* b3 = b2 + kstep;
;             if constexpr (SP2) {
;             PG8_LDB(B0, 0, 0); PG8_LDB(B1, 0, 1); PG8_SCHED; PG8_LDA(At, 0, 0); PG8_STAGE(PG8_SA(1, 1), a1 + hstep, voffA);
;             PG8_WAIT_V(8); PG8_WAIT_L(0); PG8_BAR; PG8_MMA(0, 0, At, B0); PG8_MMA(0, 1, At, B1); PG8_BAR; PG8_SCHED;
;             PG8_LDA(At, 0, 1); PG8_STAGE(PG8_SB(0, 0), b2, voffB); PG8_STAGE(PG8_SB(0, 1), b2 + hstep, voffB); PG8_STAGE(PG8_SA(0, 0), a2, voffA);
;             PG8_WAIT_V(8); PG8_WAIT_L(0); PG8_BAR; PG8_MMA(1, 0, At, B0); PG8_MMA(1, 1, At, B1); PG8_BAR; PG8_SCHED;
;             PG8_LDB(B0, 1, 0); PG8_LDB(B1, 1, 1); PG8_SCHED; PG8_LDA(At, 1, 0); PG8_STAGE(PG8_SA(0, 1), a2 + hstep, voffA);
;             PG8_WAIT_V(8); PG8_WAIT_L(0); PG8_BAR; PG8_MMA(0, 0, At, B0); PG8_MMA(0, 1, At, B1); PG8_BAR; PG8_SCHED;
;             PG8_LDA(At, 1, 1); PG8_STAGE(PG8_SB(1, 0), b3, voffB); PG8_STAGE(PG8_SB(1, 1), b3 + hstep, voffB); PG8_STAGE(PG8_SA(1, 0), a3, voffA);
;             PG8_WAIT_V(8); PG8_WAIT_L(0); PG8_BAR; PG8_MMA(1, 0, At, B0); PG8_MMA(1, 1, At, B1); PG8_BAR; PG8_SCHED;
.LBB0_484:
	ds_read_b128 v[18:21], v196
	ds_read_b128 v[22:25], v196 offset:16
	ds_read_b128 v[26:29], v196 offset:2048
	ds_read_b128 v[30:33], v196 offset:2064
	ds_read_b128 v[2:5], v197
	ds_read_b128 v[6:9], v197 offset:16
	ds_read_b128 v[10:13], v197 offset:2048
	ds_read_b128 v[14:17], v197 offset:2064
	s_add_u32 s54, s46, 0xfffc0080
	s_addc_u32 s55, s47, -1
	s_cmp_eq_u32 s75, 12
	s_cselect_b32 s57, s1, s55
	s_cselect_b32 s56, s27, s54
	s_cselect_b32 s55, s37, s74
	s_cselect_b32 s54, s43, s73
	v_lshl_add_u64 v[230:231], s[46:47], 0, v[172:173]
	s_add_i32 m0, s13, 0xc000
	ds_read_b128 v[180:183], v198
	ds_read_b128 v[184:187], v198 offset:16
	ds_read_b128 v[206:209], v198 offset:2048
	ds_read_b128 v[210:213], v198 offset:2064
	ds_read_b128 v[214:217], v198 offset:4096
	ds_read_b128 v[218:221], v198 offset:4112
	ds_read_b128 v[222:225], v198 offset:6144
	ds_read_b128 v[226:229], v198 offset:6160
	global_load_lds_dwordx4 v[230:231], off
	v_lshl_add_u64 v[230:231], s[46:47], 0, v[174:175]
	s_add_i32 m0, s13, 0xe000
	s_nop 0
	global_load_lds_dwordx4 v[230:231], off
	s_waitcnt vmcnt(8)
	s_waitcnt lgkmcnt(0)
	s_barrier
	s_setprio 1
	s_waitcnt lgkmcnt(0)
	v_mfma_f32_16x16x128_f8f6f4 v[158:161], v[18:25], v[180:187], v[158:161]
	v_mfma_f32_16x16x128_f8f6f4 v[154:157], v[26:33], v[180:187], v[154:157]
	v_mfma_f32_16x16x128_f8f6f4 v[142:145], v[18:25], v[206:213], v[142:145]
	v_mfma_f32_16x16x128_f8f6f4 v[138:141], v[26:33], v[206:213], v[138:141]
	v_mfma_f32_16x16x128_f8f6f4 v[126:129], v[18:25], v[214:221], v[126:129]
	v_mfma_f32_16x16x128_f8f6f4 v[122:125], v[26:33], v[214:221], v[122:125]
	v_mfma_f32_16x16x128_f8f6f4 v[110:113], v[18:25], v[222:229], v[110:113]
	v_mfma_f32_16x16x128_f8f6f4 v[106:109], v[26:33], v[222:229], v[106:109]
	s_setprio 0
	s_setprio 1
	v_mfma_f32_16x16x128_f8f6f4 v[150:153], v[2:9], v[180:187], v[150:153]
	v_mfma_f32_16x16x128_f8f6f4 v[146:149], v[10:17], v[180:187], v[146:149]
	v_mfma_f32_16x16x128_f8f6f4 v[134:137], v[2:9], v[206:213], v[134:137]
	v_mfma_f32_16x16x128_f8f6f4 v[130:133], v[10:17], v[206:213], v[130:133]
	v_mfma_f32_16x16x128_f8f6f4 v[118:121], v[2:9], v[214:221], v[118:121]
	v_mfma_f32_16x16x128_f8f6f4 v[114:117], v[10:17], v[214:221], v[114:117]
	v_mfma_f32_16x16x128_f8f6f4 v[102:105], v[2:9], v[222:229], v[102:105]
	v_mfma_f32_16x16x128_f8f6f4 v[98:101], v[10:17], v[222:229], v[98:101]
	s_setprio 0
	s_barrier
	s_add_i32 s76, s59, s12
	v_lshl_add_u64 v[180:181], s[54:55], 0, v[164:165]
	s_mov_b32 m0, s76
	ds_read_b128 v[206:209], v198 offset:16384
	ds_read_b128 v[210:213], v198 offset:16400
	ds_read_b128 v[214:217], v198 offset:18432
	ds_read_b128 v[218:221], v198 offset:18448
	ds_read_b128 v[222:225], v198 offset:20480
	ds_read_b128 v[226:229], v198 offset:20496
	ds_read_b128 v[230:233], v198 offset:22528
	ds_read_b128 v[234:237], v198 offset:22544
	global_load_lds_dwordx4 v[180:181], off
	s_add_i32 m0, s76, 0x2000
	s_add_u32 s76, s54, 0x40000
	v_lshl_add_u64 v[182:183], s[54:55], 0, v[168:169]
	s_addc_u32 s77, s55, 0
	s_add_i32 s84, s60, s12
	global_load_lds_dwordx4 v[182:183], off
	v_lshl_add_u64 v[184:185], s[76:77], 0, v[164:165]
	s_mov_b32 m0, s84
	v_lshl_add_u64 v[186:187], s[56:57], 0, v[166:167]
	global_load_lds_dwordx4 v[184:185], off
	v_lshl_add_u64 v[184:185], s[76:77], 0, v[168:169]
	s_add_i32 m0, s84, 0x2000
	s_nop 0
	global_load_lds_dwordx4 v[184:185], off
	v_lshl_add_u64 v[184:185], s[56:57], 0, v[162:163]
	s_mov_b32 m0, s13
	s_nop 0
	global_load_lds_dwordx4 v[184:185], off
	s_mov_b32 m0, s18
	s_nop 0
	global_load_lds_dwordx4 v[186:187], off
	s_waitcnt vmcnt(8)
	s_waitcnt lgkmcnt(0)
	s_barrier
	s_setprio 1
	s_waitcnt lgkmcnt(0)
	v_mfma_f32_16x16x128_f8f6f4 v[94:97], v[18:25], v[206:213], v[94:97]
	v_mfma_f32_16x16x128_f8f6f4 v[90:93], v[26:33], v[206:213], v[90:93]
	v_mfma_f32_16x16x128_f8f6f4 v[78:81], v[18:25], v[214:221], v[78:81]
	v_mfma_f32_16x16x128_f8f6f4 v[74:77], v[26:33], v[214:221], v[74:77]
	v_mfma_f32_16x16x128_f8f6f4 v[62:65], v[18:25], v[222:229], v[62:65]
	v_mfma_f32_16x16x128_f8f6f4 v[58:61], v[26:33], v[222:229], v[58:61]
	v_mfma_f32_16x16x128_f8f6f4 v[46:49], v[18:25], v[230:237], v[46:49]
	v_mfma_f32_16x16x128_f8f6f4 v[42:45], v[26:33], v[230:237], v[42:45]
	s_setprio 0
	s_setprio 1
	v_mfma_f32_16x16x128_f8f6f4 v[86:89], v[2:9], v[206:213], v[86:89]
	v_mfma_f32_16x16x128_f8f6f4 v[82:85], v[10:17], v[206:213], v[82:85]
	v_mfma_f32_16x16x128_f8f6f4 v[70:73], v[2:9], v[214:221], v[70:73]
	v_mfma_f32_16x16x128_f8f6f4 v[66:69], v[10:17], v[214:221], v[66:69]
	v_mfma_f32_16x16x128_f8f6f4 v[54:57], v[2:9], v[222:229], v[54:57]
	v_mfma_f32_16x16x128_f8f6f4 v[50:53], v[10:17], v[222:229], v[50:53]
	v_mfma_f32_16x16x128_f8f6f4 v[38:41], v[2:9], v[230:237], v[38:41]
	v_mfma_f32_16x16x128_f8f6f4 v[34:37], v[10:17], v[230:237], v[34:37]
	s_setprio 0
	s_barrier
; #define PG8_STAGE(bufoff, gbase, voff) do { _Pragma("unroll") for (int _i = 0; _i < 2; ++_i) \
;         __builtin_amdgcn_global_load_lds((const unsigned*)((const char*)(gbase) + (voff)[_i]), (LAS unsigned*)(lds + (bufoff) + ldsw + _i * 8192), 16, 0, 0); } while (0)
; #define PG8_LDA(dst, b, h) do { _Pragma("unroll") for (int m = 0; m < 4; ++m) _Pragma("unroll") for (int k = 0; k < 2; ++k) dst[m][k] = *(const LAS bf16x8*)(lds + PG8_SA(b, h) + aoff + m * 2048 + k * 1024); } while (0)
; #define PG8_LDB(dst, b, h) do { _Pragma("unroll") for (int n = 0; n < 2; ++n) _Pragma("unroll") for (int k = 0; k < 2; ++k) dst[n][k] = *(const LAS bf16x8*)(lds + PG8_SB(b, h) + boff + n * 2048 + k * 1024); } while (0)
; #define PG8_WAIT_V(n) asm volatile("s_waitcnt vmcnt(" #n ")" ::: "memory")
; template <class Epi, class Sched, bool ALIGN_EPI, bool SP2>
; __device__ __forceinline__ void gemm_phase8(LAS unsigned char* lds, const int K, const Sched& S, const Epi& E) {
;     ...
;         for (int t = 0; t < nt; t += 2) {
;             const bool last = (t == nt - 2);
;             const char* a1 = cA + (size_t)(t + 1) * kstep;
;             const char* a2 = last ? nA : cA + (size_t)(t + 2) * kstep; const char* b2 = last ? nB : cB + (size_t)(t + 2) * kstep;
;             const char* a3 = a2 + kstep; const char* b3 = b2 + kstep;
;             if constexpr (SP2) {
;             PG8_LDB(B0, 0, 0); PG8_LDB(B1, 0, 1); PG8_SCHED; PG8_LDA(At, 0, 0); PG8_STAGE(PG8_SA(1, 1), a1 + hstep, voffA);
;             PG8_WAIT_V(8); PG8_WAIT_L(0); PG8_BAR; PG8_MMA(0, 0, At, B0); PG8_MMA(0, 1, At, B1); PG8_BAR; PG8_SCHED;
;             PG8_LDA(At, 0, 1); PG8_STAGE(PG8_SB(0, 0), b2, voffB); PG8_STAGE(PG8_SB(0, 1), b2 + hstep, voffB); PG8_STAGE(PG8_SA(0, 0), a2, voffA);
;             PG8_WAIT_V(8); PG8_WAIT_L(0); PG8_BAR; PG8_MMA(1, 0, At, B0); PG8_MMA(1, 1, At, B1); PG8_BAR; PG8_SCHED;
;             PG8_LDB(B0, 1, 0); PG8_LDB(B1, 1, 1); PG8_SCHED; PG8_LDA(At, 1, 0); PG8_STAGE(PG8_SA(0, 1), a2 + hstep, voffA);
;             PG8_WAIT_V(8); PG8_WAIT_L(0); PG8_BAR; PG8_MMA(0, 0, At, B0); PG8_MMA(0, 1, At, B1); PG8_BAR; PG8_SCHED;
;             PG8_LDA(At, 1, 1); PG8_STAGE(PG8_SB(1, 0), b3, voffB); PG8_STAGE(PG8_SB(1, 1), b3 + hstep, voffB); PG8_STAGE(PG8_SA(1, 0), a3, voffA);
;             PG8_WAIT_V(8); PG8_WAIT_L(0); PG8_BAR; PG8_MMA(1, 0, At, B0); PG8_MMA(1, 1, At, B1); PG8_BAR; PG8_SCHED;
	s_add_i32 s76, 0, 0x18000
	s_add_i32 s77, 0, 0x1c000
	v_add_u32_e32 v14, s76, v194
	v_add_u32_e32 v30, s77, v194
	ds_read_b128 v[2:5], v14
	ds_read_b128 v[6:9], v14 offset:16
	ds_read_b128 v[10:13], v14 offset:2048
	ds_read_b128 v[14:17], v14 offset:2064
	ds_read_b128 v[18:21], v30
	ds_read_b128 v[22:25], v30 offset:16
	ds_read_b128 v[26:29], v30 offset:2048
	ds_read_b128 v[30:33], v30 offset:2064
	s_add_u32 s56, s56, 0x40000
	s_addc_u32 s57, s57, 0
	s_mov_b32 m0, s19
	v_lshl_add_u64 v[238:239], s[56:57], 0, v[162:163]
	ds_read_b128 v[206:209], v198 offset:32768
	ds_read_b128 v[210:213], v198 offset:32784
	ds_read_b128 v[214:217], v198 offset:34816
	ds_read_b128 v[218:221], v198 offset:34832
	ds_read_b128 v[222:225], v198 offset:36864
	ds_read_b128 v[226:229], v198 offset:36880
	ds_read_b128 v[230:233], v198 offset:38912
	ds_read_b128 v[234:237], v198 offset:38928
	global_load_lds_dwordx4 v[238:239], off
	v_lshl_add_u64 v[238:239], s[56:57], 0, v[166:167]
	s_mov_b32 m0, s23
	s_nop 0
	global_load_lds_dwordx4 v[238:239], off
	s_waitcnt vmcnt(8)
	s_waitcnt lgkmcnt(0)
	s_barrier
	s_setprio 1
	s_waitcnt lgkmcnt(0)
	v_mfma_f32_16x16x128_f8f6f4 v[158:161], v[2:9], v[206:213], v[158:161]
	v_mfma_f32_16x16x128_f8f6f4 v[154:157], v[10:17], v[206:213], v[154:157]
	v_mfma_f32_16x16x128_f8f6f4 v[142:145], v[2:9], v[214:221], v[142:145]
	v_mfma_f32_16x16x128_f8f6f4 v[138:141], v[10:17], v[214:221], v[138:141]
	v_mfma_f32_16x16x128_f8f6f4 v[126:129], v[2:9], v[222:229], v[126:129]
	v_mfma_f32_16x16x128_f8f6f4 v[122:125], v[10:17], v[222:229], v[122:125]
	v_mfma_f32_16x16x128_f8f6f4 v[110:113], v[2:9], v[230:237], v[110:113]
	v_mfma_f32_16x16x128_f8f6f4 v[106:109], v[10:17], v[230:237], v[106:109]
	s_setprio 0
	s_setprio 1
	v_mfma_f32_16x16x128_f8f6f4 v[150:153], v[18:25], v[206:213], v[150:153]
	v_mfma_f32_16x16x128_f8f6f4 v[146:149], v[26:33], v[206:213], v[146:149]
	v_mfma_f32_16x16x128_f8f6f4 v[134:137], v[18:25], v[214:221], v[134:137]
	v_mfma_f32_16x16x128_f8f6f4 v[130:133], v[26:33], v[214:221], v[130:133]
	v_mfma_f32_16x16x128_f8f6f4 v[118:121], v[18:25], v[222:229], v[118:121]
	v_mfma_f32_16x16x128_f8f6f4 v[114:117], v[26:33], v[222:229], v[114:117]
	v_mfma_f32_16x16x128_f8f6f4 v[102:105], v[18:25], v[230:237], v[102:105]
	v_mfma_f32_16x16x128_f8f6f4 v[98:101], v[26:33], v[230:237], v[98:101]
	s_setprio 0
	s_barrier
	s_add_i32 s56, s76, s12
	v_lshl_add_u64 v[180:181], v[180:181], 0, s[8:9]
	s_mov_b32 m0, s56
	ds_read_b128 v[206:209], v198 offset:49152
	ds_read_b128 v[210:213], v198 offset:49168
	ds_read_b128 v[214:217], v198 offset:51200
	ds_read_b128 v[218:221], v198 offset:51216
	ds_read_b128 v[222:225], v198 offset:53248
	ds_read_b128 v[226:229], v198 offset:53264
	ds_read_b128 v[230:233], v198 offset:55296
	ds_read_b128 v[234:237], v198 offset:55312
	global_load_lds_dwordx4 v[180:181], off
	s_add_i32 m0, s56, 0x2000
	s_add_u32 s54, s54, 0x40080
	v_lshl_add_u64 v[180:181], v[182:183], 0, s[8:9]
	s_addc_u32 s55, s55, 0
	s_add_i32 s56, s77, s12
	global_load_lds_dwordx4 v[180:181], off
	v_lshl_add_u64 v[180:181], s[54:55], 0, v[164:165]
	s_mov_b32 m0, s56
	s_nop 0
	global_load_lds_dwordx4 v[180:181], off
	v_lshl_add_u64 v[180:181], s[54:55], 0, v[168:169]
	s_add_i32 m0, s56, 0x2000
	s_nop 0
	global_load_lds_dwordx4 v[180:181], off
	v_lshl_add_u64 v[180:181], v[184:185], 0, s[8:9]
	s_mov_b32 m0, s33
	s_nop 0
	global_load_lds_dwordx4 v[180:181], off
	v_lshl_add_u64 v[180:181], v[186:187], 0, s[8:9]
	s_mov_b32 m0, s58
	s_nop 0
	global_load_lds_dwordx4 v[180:181], off
	s_waitcnt vmcnt(8)
	s_waitcnt lgkmcnt(0)
	s_barrier
	s_setprio 1
	s_waitcnt lgkmcnt(0)
	v_mfma_f32_16x16x128_f8f6f4 v[94:97], v[2:9], v[206:213], v[94:97]
	v_mfma_f32_16x16x128_f8f6f4 v[90:93], v[10:17], v[206:213], v[90:93]
	v_mfma_f32_16x16x128_f8f6f4 v[78:81], v[2:9], v[214:221], v[78:81]
	v_mfma_f32_16x16x128_f8f6f4 v[74:77], v[10:17], v[214:221], v[74:77]
	v_mfma_f32_16x16x128_f8f6f4 v[62:65], v[2:9], v[222:229], v[62:65]
	v_mfma_f32_16x16x128_f8f6f4 v[58:61], v[10:17], v[222:229], v[58:61]
	v_mfma_f32_16x16x128_f8f6f4 v[46:49], v[2:9], v[230:237], v[46:49]
	v_mfma_f32_16x16x128_f8f6f4 v[42:45], v[10:17], v[230:237], v[42:45]
	s_setprio 0
	s_setprio 1
	v_mfma_f32_16x16x128_f8f6f4 v[86:89], v[18:25], v[206:213], v[86:89]
	v_mfma_f32_16x16x128_f8f6f4 v[82:85], v[26:33], v[206:213], v[82:85]
	v_mfma_f32_16x16x128_f8f6f4 v[70:73], v[18:25], v[214:221], v[70:73]
	v_mfma_f32_16x16x128_f8f6f4 v[66:69], v[26:33], v[214:221], v[66:69]
	v_mfma_f32_16x16x128_f8f6f4 v[54:57], v[18:25], v[222:229], v[54:57]
	v_mfma_f32_16x16x128_f8f6f4 v[50:53], v[26:33], v[222:229], v[50:53]
	v_mfma_f32_16x16x128_f8f6f4 v[38:41], v[18:25], v[230:237], v[38:41]
	v_mfma_f32_16x16x128_f8f6f4 v[34:37], v[26:33], v[230:237], v[34:37]
	s_setprio 0
	s_barrier
	s_add_i32 s75, s75, 2
	s_add_u32 s46, s46, 0x100
	s_addc_u32 s47, s47, 0
	s_add_u32 s73, s73, 0x100
	s_addc_u32 s74, s74, 0
	s_cmp_gt_u32 s75, 13
	s_cbranch_scc0 .LBB0_484
	s_and_b64 vcc, exec, s[10:11]
	s_cbranch_vccz .LBB0_487
	s_barrier

; #define PG8_STAGE(bufoff, gbase, voff) do { _Pragma("unroll") for (int _i = 0; _i < 2; ++_i) \
;         __builtin_amdgcn_global_load_lds((const unsigned*)((const char*)(gbase) + (voff)[_i]), (LAS unsigned*)(lds + (bufoff) + ldsw + _i * 8192), 16, 0, 0); } while (0)
; #define PG8_LDA(dst, b, h) do { _Pragma("unroll") for (int m = 0; m < 4; ++m) _Pragma("unroll") for (int k = 0; k < 2; ++k) dst[m][k] = *(const LAS bf16x8*)(lds + PG8_SA(b, h) + aoff + m * 2048 + k * 1024); } while (0)
; #define PG8_LDB(dst, b, h) do { _Pragma("unroll") for (int n = 0; n < 2; ++n) _Pragma("unroll") for (int k = 0; k < 2; ++k) dst[n][k] = *(const LAS bf16x8*)(lds + PG8_SB(b, h) + boff + n * 2048 + k * 1024); } while (0)
; #define PG8_MMA(ai, bj, At, Bt) do { __builtin_amdgcn_s_setprio(1); _Pragma("unroll") for (int m = 0; m < 4; ++m) _Pragma("unroll") for (int n = 0; n < 2; ++n) _Pragma("unroll") for (int k = 0; k < 2; ++k) \
;         acc[ai][bj][m][n] = __builtin_amdgcn_mfma_f32_16x16x32_bf16(Bt[n][k], At[m][k], acc[ai][bj][m][n], 0, 0, 0); __builtin_amdgcn_s_setprio(0); } while (0)
; #define PG8_WAIT_V(n) asm volatile("s_waitcnt vmcnt(" #n ")" ::: "memory")
; #define PG8_WAIT_L(n) asm volatile("s_waitcnt lgkmcnt(" #n ")" ::: "memory")
; #define PG8_BAR __builtin_amdgcn_s_barrier()
; #define PG8_SCHED __builtin_amdgcn_sched_barrier(0)
; #define PG8_STAGE(bufoff, gbase, voff) do { _Pragma("unroll") for (int _i = 0; _i < 2; ++_i) \
;         __builtin_amdgcn_global_load_lds((const unsigned*)((const char*)(gbase) + (voff)[_i]), (LAS unsigned*)(lds + (bufoff) + ldsw + _i * 8192), 16, 0, 0); } while (0)
; #define PG8_BAR __builtin_amdgcn_s_barrier()
; template <class Epi, class Sched, bool ALIGN_EPI, bool SP2>
; __device__ __forceinline__ void gemm_phase8(LAS unsigned char* lds, const int K, const Sched& S, const Epi& E) {
;     ...
;             if constexpr (SP2) {
;             PG8_LDB(B0, 0, 0); PG8_LDB(B1, 0, 1); PG8_SCHED; PG8_LDA(At, 0, 0); PG8_STAGE(PG8_SA(1, 1), a1 + hstep, voffA);
;             PG8_WAIT_V(8); PG8_WAIT_L(0); PG8_BAR; PG8_MMA(0, 0, At, B0); PG8_MMA(0, 1, At, B1); PG8_BAR; PG8_SCHED;
;             PG8_LDA(At, 0, 1); PG8_STAGE(PG8_SB(0, 0), b2, voffB); PG8_STAGE(PG8_SB(0, 1), b2 + hstep, voffB); PG8_STAGE(PG8_SA(0, 0), a2, voffA);
;             PG8_WAIT_V(8); PG8_WAIT_L(0); PG8_BAR; PG8_MMA(1, 0, At, B0); PG8_MMA(1, 1, At, B1); PG8_BAR; PG8_SCHED;
.LBB0_567:
	ds_read_b128 v[18:21], v190
	ds_read_b128 v[22:25], v190 offset:16
	ds_read_b128 v[26:29], v190 offset:2048
	ds_read_b128 v[30:33], v190 offset:2064
	ds_read_b128 v[2:5], v191
	ds_read_b128 v[6:9], v191 offset:16
	ds_read_b128 v[10:13], v191 offset:2048
	ds_read_b128 v[14:17], v191 offset:2064
	s_add_u32 s54, s46, 0xfffc0080
	s_addc_u32 s55, s47, -1
	s_cmp_eq_u32 s76, 12
	s_cselect_b32 s57, s1, s55
	s_cselect_b32 s56, s37, s54
	s_cselect_b32 s55, s27, s75
	s_cselect_b32 s54, s43, s74
	v_lshl_add_u64 v[220:221], s[46:47], 0, v[172:173]
	s_add_i32 m0, s13, 0xc000
	ds_read_b128 v[180:183], v194
	ds_read_b128 v[184:187], v194 offset:16
	ds_read_b128 v[196:199], v194 offset:2048
	ds_read_b128 v[200:203], v194 offset:2064
	ds_read_b128 v[204:207], v194 offset:4096
	ds_read_b128 v[208:211], v194 offset:4112
	ds_read_b128 v[212:215], v194 offset:6144
	ds_read_b128 v[216:219], v194 offset:6160
	global_load_lds_dwordx4 v[220:221], off
	v_lshl_add_u64 v[220:221], s[46:47], 0, v[174:175]
	s_add_i32 m0, s13, 0xe000
	s_nop 0
	global_load_lds_dwordx4 v[220:221], off
	s_waitcnt vmcnt(8)
	s_waitcnt lgkmcnt(0)
	s_barrier
	s_setprio 1
	s_waitcnt lgkmcnt(0)
	v_mfma_f32_16x16x128_f8f6f4 v[158:161], v[18:25], v[180:187], v[158:161]
	v_mfma_f32_16x16x128_f8f6f4 v[154:157], v[26:33], v[180:187], v[154:157]
	v_mfma_f32_16x16x128_f8f6f4 v[142:145], v[18:25], v[196:203], v[142:145]
	v_mfma_f32_16x16x128_f8f6f4 v[138:141], v[26:33], v[196:203], v[138:141]
	v_mfma_f32_16x16x128_f8f6f4 v[126:129], v[18:25], v[204:211], v[126:129]
	v_mfma_f32_16x16x128_f8f6f4 v[122:125], v[26:33], v[204:211], v[122:125]
	v_mfma_f32_16x16x128_f8f6f4 v[110:113], v[18:25], v[212:219], v[110:113]
	v_mfma_f32_16x16x128_f8f6f4 v[106:109], v[26:33], v[212:219], v[106:109]
	s_setprio 0
	s_setprio 1
	v_mfma_f32_16x16x128_f8f6f4 v[150:153], v[2:9], v[180:187], v[150:153]
	v_mfma_f32_16x16x128_f8f6f4 v[146:149], v[10:17], v[180:187], v[146:149]
	v_mfma_f32_16x16x128_f8f6f4 v[134:137], v[2:9], v[196:203], v[134:137]
	v_mfma_f32_16x16x128_f8f6f4 v[130:133], v[10:17], v[196:203], v[130:133]
	v_mfma_f32_16x16x128_f8f6f4 v[118:121], v[2:9], v[204:211], v[118:121]
	v_mfma_f32_16x16x128_f8f6f4 v[114:117], v[10:17], v[204:211], v[114:117]
	v_mfma_f32_16x16x128_f8f6f4 v[102:105], v[2:9], v[212:219], v[102:105]
	v_mfma_f32_16x16x128_f8f6f4 v[98:101], v[10:17], v[212:219], v[98:101]
	s_setprio 0
	s_barrier
	s_add_i32 s77, s60, s12
	v_lshl_add_u64 v[180:181], s[54:55], 0, v[164:165]
	s_mov_b32 m0, s77
	ds_read_b128 v[196:199], v194 offset:16384
	ds_read_b128 v[200:203], v194 offset:16400
	ds_read_b128 v[204:207], v194 offset:18432
	ds_read_b128 v[208:211], v194 offset:18448
	ds_read_b128 v[212:215], v194 offset:20480
	ds_read_b128 v[216:219], v194 offset:20496
	ds_read_b128 v[220:223], v194 offset:22528
	ds_read_b128 v[224:227], v194 offset:22544
	global_load_lds_dwordx4 v[180:181], off
	s_add_i32 m0, s77, 0x2000
	s_add_u32 s84, s54, 0x40000
	v_lshl_add_u64 v[182:183], s[54:55], 0, v[168:169]
	s_addc_u32 s85, s55, 0
	s_add_i32 s77, s61, s12
	global_load_lds_dwordx4 v[182:183], off
	v_lshl_add_u64 v[184:185], s[84:85], 0, v[164:165]
	s_mov_b32 m0, s77
	v_lshl_add_u64 v[186:187], s[56:57], 0, v[166:167]
	global_load_lds_dwordx4 v[184:185], off
	v_lshl_add_u64 v[184:185], s[84:85], 0, v[168:169]
	s_add_i32 m0, s77, 0x2000
	s_nop 0
	global_load_lds_dwordx4 v[184:185], off
	v_lshl_add_u64 v[184:185], s[56:57], 0, v[162:163]
	s_mov_b32 m0, s13
	s_nop 0
	global_load_lds_dwordx4 v[184:185], off
	s_mov_b32 m0, s18
	s_nop 0
	global_load_lds_dwordx4 v[186:187], off
	s_waitcnt vmcnt(8)
	s_waitcnt lgkmcnt(0)
	s_barrier
	s_setprio 1
	s_waitcnt lgkmcnt(0)
	v_mfma_f32_16x16x128_f8f6f4 v[94:97], v[18:25], v[196:203], v[94:97]
	v_mfma_f32_16x16x128_f8f6f4 v[90:93], v[26:33], v[196:203], v[90:93]
	v_mfma_f32_16x16x128_f8f6f4 v[78:81], v[18:25], v[204:211], v[78:81]
	v_mfma_f32_16x16x128_f8f6f4 v[74:77], v[26:33], v[204:211], v[74:77]
	v_mfma_f32_16x16x128_f8f6f4 v[62:65], v[18:25], v[212:219], v[62:65]
	v_mfma_f32_16x16x128_f8f6f4 v[58:61], v[26:33], v[212:219], v[58:61]
	v_mfma_f32_16x16x128_f8f6f4 v[46:49], v[18:25], v[220:227], v[46:49]
	v_mfma_f32_16x16x128_f8f6f4 v[42:45], v[26:33], v[220:227], v[42:45]
	s_setprio 0
	s_setprio 1
	v_mfma_f32_16x16x128_f8f6f4 v[86:89], v[2:9], v[196:203], v[86:89]
	v_mfma_f32_16x16x128_f8f6f4 v[82:85], v[10:17], v[196:203], v[82:85]
	v_mfma_f32_16x16x128_f8f6f4 v[70:73], v[2:9], v[204:211], v[70:73]
	v_mfma_f32_16x16x128_f8f6f4 v[66:69], v[10:17], v[204:211], v[66:69]
	v_mfma_f32_16x16x128_f8f6f4 v[54:57], v[2:9], v[212:219], v[54:57]
	v_mfma_f32_16x16x128_f8f6f4 v[50:53], v[10:17], v[212:219], v[50:53]
	v_mfma_f32_16x16x128_f8f6f4 v[38:41], v[2:9], v[220:227], v[38:41]
	v_mfma_f32_16x16x128_f8f6f4 v[34:37], v[10:17], v[220:227], v[34:37]
	s_setprio 0
	s_barrier
; #define PG8_STAGE(bufoff, gbase, voff) do { _Pragma("unroll") for (int _i = 0; _i < 2; ++_i) \
;         __builtin_amdgcn_global_load_lds((const unsigned*)((const char*)(gbase) + (voff)[_i]), (LAS unsigned*)(lds + (bufoff) + ldsw + _i * 8192), 16, 0, 0); } while (0)
; #define PG8_LDA(dst, b, h) do { _Pragma("unroll") for (int m = 0; m < 4; ++m) _Pragma("unroll") for (int k = 0; k < 2; ++k) dst[m][k] = *(const LAS bf16x8*)(lds + PG8_SA(b, h) + aoff + m * 2048 + k * 1024); } while (0)
; #define PG8_LDB(dst, b, h) do { _Pragma("unroll") for (int n = 0; n < 2; ++n) _Pragma("unroll") for (int k = 0; k < 2; ++k) dst[n][k] = *(const LAS bf16x8*)(lds + PG8_SB(b, h) + boff + n * 2048 + k * 1024); } while (0)
; #define PG8_MMA(ai, bj, At, Bt) do { __builtin_amdgcn_s_setprio(1); _Pragma("unroll") for (int m = 0; m < 4; ++m) _Pragma("unroll") for (int n = 0; n < 2; ++n) _Pragma("unroll") for (int k = 0; k < 2; ++k) \
;         acc[ai][bj][m][n] = __builtin_amdgcn_mfma_f32_16x16x32_bf16(Bt[n][k], At[m][k], acc[ai][bj][m][n], 0, 0, 0); __builtin_amdgcn_s_setprio(0); } while (0)
; #define PG8_WAIT_V(n) asm volatile("s_waitcnt vmcnt(" #n ")" ::: "memory")
; #define PG8_WAIT_L(n) asm volatile("s_waitcnt lgkmcnt(" #n ")" ::: "memory")
; #define PG8_BAR __builtin_amdgcn_s_barrier()
; #define PG8_SCHED __builtin_amdgcn_sched_barrier(0)
; template <class Epi, class Sched, bool ALIGN_EPI, bool SP2>
; __device__ __forceinline__ void gemm_phase8(LAS unsigned char* lds, const int K, const Sched& S, const Epi& E) {
;     ...
;         for (int t = 0; t < nt; t += 2) {
;             const bool last = (t == nt - 2);
;             const char* a1 = cA + (size_t)(t + 1) * kstep;
;             const char* a2 = last ? nA : cA + (size_t)(t + 2) * kstep; const char* b2 = last ? nB : cB + (size_t)(t + 2) * kstep;
;             const char* a3 = a2 + kstep; const char* b3 = b2 + kstep;
;     ...
;             PG8_LDB(B0, 1, 0); PG8_LDB(B1, 1, 1); PG8_SCHED; PG8_LDA(At, 1, 0); PG8_STAGE(PG8_SA(0, 1), a2 + hstep, voffA);
;             PG8_WAIT_V(8); PG8_WAIT_L(0); PG8_BAR; PG8_MMA(0, 0, At, B0); PG8_MMA(0, 1, At, B1); PG8_BAR; PG8_SCHED;
;             PG8_LDA(At, 1, 1); PG8_STAGE(PG8_SB(1, 0), b3, voffB); PG8_STAGE(PG8_SB(1, 1), b3 + hstep, voffB); PG8_STAGE(PG8_SA(1, 0), a3, voffA);
;             PG8_WAIT_V(8); PG8_WAIT_L(0); PG8_BAR; PG8_MMA(1, 0, At, B0); PG8_MMA(1, 1, At, B1); PG8_BAR; PG8_SCHED;
	s_add_i32 s77, 0, 0x18000
	s_add_i32 s84, 0, 0x1c000
	v_add_u32_e32 v14, s77, v188
	v_add_u32_e32 v30, s84, v188
	ds_read_b128 v[2:5], v14
	ds_read_b128 v[6:9], v14 offset:16
	ds_read_b128 v[10:13], v14 offset:2048
	ds_read_b128 v[14:17], v14 offset:2064
	ds_read_b128 v[18:21], v30
	ds_read_b128 v[22:25], v30 offset:16
	ds_read_b128 v[26:29], v30 offset:2048
	ds_read_b128 v[30:33], v30 offset:2064
	s_add_u32 s56, s56, 0x40000
	s_addc_u32 s57, s57, 0
	s_mov_b32 m0, s19
	v_lshl_add_u64 v[228:229], s[56:57], 0, v[162:163]
	ds_read_b128 v[196:199], v194 offset:32768
	ds_read_b128 v[200:203], v194 offset:32784
	ds_read_b128 v[204:207], v194 offset:34816
	ds_read_b128 v[208:211], v194 offset:34832
	ds_read_b128 v[212:215], v194 offset:36864
	ds_read_b128 v[216:219], v194 offset:36880
	ds_read_b128 v[220:223], v194 offset:38912
	ds_read_b128 v[224:227], v194 offset:38928
	global_load_lds_dwordx4 v[228:229], off
	v_lshl_add_u64 v[228:229], s[56:57], 0, v[166:167]
	s_mov_b32 m0, s23
	s_nop 0
	global_load_lds_dwordx4 v[228:229], off
	s_waitcnt vmcnt(8)
	s_waitcnt lgkmcnt(0)
	s_barrier
	s_setprio 1
	s_waitcnt lgkmcnt(0)
	v_mfma_f32_16x16x128_f8f6f4 v[158:161], v[2:9], v[196:203], v[158:161]
	v_mfma_f32_16x16x128_f8f6f4 v[154:157], v[10:17], v[196:203], v[154:157]
	v_mfma_f32_16x16x128_f8f6f4 v[142:145], v[2:9], v[204:211], v[142:145]
	v_mfma_f32_16x16x128_f8f6f4 v[138:141], v[10:17], v[204:211], v[138:141]
	v_mfma_f32_16x16x128_f8f6f4 v[126:129], v[2:9], v[212:219], v[126:129]
	v_mfma_f32_16x16x128_f8f6f4 v[122:125], v[10:17], v[212:219], v[122:125]
	v_mfma_f32_16x16x128_f8f6f4 v[110:113], v[2:9], v[220:227], v[110:113]
	v_mfma_f32_16x16x128_f8f6f4 v[106:109], v[10:17], v[220:227], v[106:109]
	s_setprio 0
	s_setprio 1
	v_mfma_f32_16x16x128_f8f6f4 v[150:153], v[18:25], v[196:203], v[150:153]
	v_mfma_f32_16x16x128_f8f6f4 v[146:149], v[26:33], v[196:203], v[146:149]
	v_mfma_f32_16x16x128_f8f6f4 v[134:137], v[18:25], v[204:211], v[134:137]
	v_mfma_f32_16x16x128_f8f6f4 v[130:133], v[26:33], v[204:211], v[130:133]
	v_mfma_f32_16x16x128_f8f6f4 v[118:121], v[18:25], v[212:219], v[118:121]
	v_mfma_f32_16x16x128_f8f6f4 v[114:117], v[26:33], v[212:219], v[114:117]
	v_mfma_f32_16x16x128_f8f6f4 v[102:105], v[18:25], v[220:227], v[102:105]
	v_mfma_f32_16x16x128_f8f6f4 v[98:101], v[26:33], v[220:227], v[98:101]
	s_setprio 0
	s_barrier
	s_add_i32 s56, s77, s12
	v_lshl_add_u64 v[180:181], v[180:181], 0, s[8:9]
	s_mov_b32 m0, s56
	ds_read_b128 v[196:199], v194 offset:49152
	ds_read_b128 v[200:203], v194 offset:49168
	ds_read_b128 v[204:207], v194 offset:51200
	ds_read_b128 v[208:211], v194 offset:51216
	ds_read_b128 v[212:215], v194 offset:53248
	ds_read_b128 v[216:219], v194 offset:53264
	ds_read_b128 v[220:223], v194 offset:55296
	ds_read_b128 v[224:227], v194 offset:55312
	global_load_lds_dwordx4 v[180:181], off
	s_add_i32 m0, s56, 0x2000
	s_add_u32 s54, s54, 0x40080
	v_lshl_add_u64 v[180:181], v[182:183], 0, s[8:9]
	s_addc_u32 s55, s55, 0
	s_add_i32 s56, s84, s12
	global_load_lds_dwordx4 v[180:181], off
	v_lshl_add_u64 v[180:181], s[54:55], 0, v[164:165]
	s_mov_b32 m0, s56
	s_nop 0
	global_load_lds_dwordx4 v[180:181], off
	v_lshl_add_u64 v[180:181], s[54:55], 0, v[168:169]
	s_add_i32 m0, s56, 0x2000
	s_nop 0
	global_load_lds_dwordx4 v[180:181], off
	v_lshl_add_u64 v[180:181], v[184:185], 0, s[8:9]
	s_mov_b32 m0, s33
	s_nop 0
	global_load_lds_dwordx4 v[180:181], off
	v_lshl_add_u64 v[180:181], v[186:187], 0, s[8:9]
	s_mov_b32 m0, s58
	s_nop 0
	global_load_lds_dwordx4 v[180:181], off
	s_waitcnt vmcnt(8)
	s_waitcnt lgkmcnt(0)
	s_barrier
	s_setprio 1
	s_waitcnt lgkmcnt(0)
	v_mfma_f32_16x16x128_f8f6f4 v[94:97], v[2:9], v[196:203], v[94:97]
	v_mfma_f32_16x16x128_f8f6f4 v[90:93], v[10:17], v[196:203], v[90:93]
	v_mfma_f32_16x16x128_f8f6f4 v[78:81], v[2:9], v[204:211], v[78:81]
	v_mfma_f32_16x16x128_f8f6f4 v[74:77], v[10:17], v[204:211], v[74:77]
	v_mfma_f32_16x16x128_f8f6f4 v[62:65], v[2:9], v[212:219], v[62:65]
	v_mfma_f32_16x16x128_f8f6f4 v[58:61], v[10:17], v[212:219], v[58:61]
	v_mfma_f32_16x16x128_f8f6f4 v[46:49], v[2:9], v[220:227], v[46:49]
	v_mfma_f32_16x16x128_f8f6f4 v[42:45], v[10:17], v[220:227], v[42:45]
	s_setprio 0
	s_setprio 1
	v_mfma_f32_16x16x128_f8f6f4 v[86:89], v[18:25], v[196:203], v[86:89]
	v_mfma_f32_16x16x128_f8f6f4 v[82:85], v[26:33], v[196:203], v[82:85]
	v_mfma_f32_16x16x128_f8f6f4 v[70:73], v[18:25], v[204:211], v[70:73]
	v_mfma_f32_16x16x128_f8f6f4 v[66:69], v[26:33], v[204:211], v[66:69]
	v_mfma_f32_16x16x128_f8f6f4 v[54:57], v[18:25], v[212:219], v[54:57]
	v_mfma_f32_16x16x128_f8f6f4 v[50:53], v[26:33], v[212:219], v[50:53]
	v_mfma_f32_16x16x128_f8f6f4 v[38:41], v[18:25], v[220:227], v[38:41]
	v_mfma_f32_16x16x128_f8f6f4 v[34:37], v[26:33], v[220:227], v[34:37]
	s_setprio 0
	s_barrier
	s_add_i32 s76, s76, 2
	s_add_u32 s46, s46, 0x100
	s_addc_u32 s47, s47, 0
	s_add_u32 s74, s74, 0x100
	s_addc_u32 s75, s75, 0
	s_cmp_gt_u32 s76, 13
	s_cbranch_scc0 .LBB0_567
	s_and_b64 vcc, exec, s[10:11]
	s_cbranch_vccz .LBB0_570
	s_barrier
